# indexer score loop: packed v_pk_fma/add_f32 between MFMAs split into scalar v_fma/v_add (asm guide 7.5), on top of v23
# baseline (speedup 1.0000x reference)
; #define IDX_MMA(BX, cA, cB) do { _Pragma("unroll") for (int s = 0; s < 4; ++s) { cA = __builtin_amdgcn_mfma_f32_32x32x16_bf16(af[s], BX[s], cA, 0, 0, 0); cB = __builtin_amdgcn_mfma_f32_32x32x16_bf16(af[s], BX[4 + s], cB, 0, 0, 0); } } while (0)
; #define IDX_LOAD(BX, i_) do { const bf16_t* kn_ = kp + (size_t)(i_) * 4096; \
;         _Pragma("unroll") for (int s = 0; s < 4; ++s) { BX[s] = *(const bf16x8*)(kn_ + 512 * s); BX[4 + s] = *(const bf16x8*)(kn_ + 2048 + 512 * s); } } while (0)
; __device__ __forceinline__ void indexer_query(Frame& F, ArgsP a, int b, int t) {
;     ...
;     bf16x8 bX[8], bY[8];
;     IDX_LOAD(bX, 0); IDX_LOAD(bY, nt > 1 ? 1 : 0);
;     for (int i = 0; i < nt; i += 2) {
;         f32x16 cA = {}, cB = {}, cC = {}, cD = {};
;         IDX_MMA(bX, cA, cB); IDX_LOAD(bX, i + 2 < nt ? i + 2 : nt - 1);
;         IDX_MMA(bY, cC, cD); IDX_LOAD(bY, i + 3 < nt ? i + 3 : nt - 1);
;         IDX_SUM(cA, cB, i); IDX_SUM(cC, cD, i + 1);
.LBB0_720:
	s_add_i32 s3, s2, -1
	s_min_i32 s24, s3, s35
	s_lshl_b64 s[0:1], s[24:25], 13
	v_lshl_add_u64 v[22:23], v[188:189], 0, s[0:1]
	v_add_co_u32_e32 v24, vcc, s34, v22
	global_load_dwordx4 v[82:85], v[22:23], off
	s_nop 0
	v_addc_co_u32_e32 v25, vcc, 0, v23, vcc
	global_load_dwordx4 v[130:133], v[24:25], off
	global_load_dwordx4 v[86:89], v[22:23], off offset:1024
	global_load_dwordx4 v[134:137], v[24:25], off offset:1024
	global_load_dwordx4 v[90:93], v[22:23], off offset:2048
	global_load_dwordx4 v[138:141], v[24:25], off offset:2048
	global_load_dwordx4 v[94:97], v[22:23], off offset:3072
	global_load_dwordx4 v[142:145], v[24:25], off offset:3072
	s_waitcnt vmcnt(8)
	v_mfma_f32_32x32x16_bf16 v[18:33], v[50:53], v[18:21], 0
	s_min_i32 s24, s2, s35
	s_lshl_b64 s[0:1], s[24:25], 13
	s_add_i32 s2, s2, 2
	s_cmp_le_i32 s3, s35
	v_mfma_f32_32x32x16_bf16 v[18:33], v[54:57], v[42:45], v[18:33]
	v_mfma_f32_32x32x16_bf16 v[18:33], v[58:61], v[38:41], v[18:33]
	v_mfma_f32_32x32x16_bf16 v[18:33], v[62:65], v[34:37], v[18:33]
	v_mfma_f32_32x32x16_bf16 v[34:49], v[50:53], v[10:13], 0
	s_nop 10
	v_max_i32_e32 v18, 0, v18
	v_max_i32_e32 v19, 0, v19
	v_fma_f32 v18, v66, v18, 0
	v_fma_f32 v19, v67, v19, 0
	v_max_i32_e32 v20, 0, v20
	v_max_i32_e32 v21, 0, v21
	v_fma_f32 v18, v68, v20, v18
	v_fma_f32 v19, v69, v21, v19
	v_max_i32_e32 v22, 0, v22
	v_mfma_f32_32x32x16_bf16 v[34:49], v[54:57], v[6:9], v[34:49]
	v_max_i32_e32 v23, 0, v23
	v_fma_f32 v18, v70, v22, v18
	v_fma_f32 v19, v71, v23, v19
	v_max_i32_e32 v22, 0, v24
	v_max_i32_e32 v23, 0, v25
	v_fma_f32 v18, v72, v22, v18
	v_fma_f32 v19, v73, v23, v19
	v_max_i32_e32 v22, 0, v26
	v_max_i32_e32 v23, 0, v27
	v_mfma_f32_32x32x16_bf16 v[34:49], v[58:61], v[2:5], v[34:49]
	v_lshl_add_u64 v[2:3], v[188:189], 0, s[0:1]
	v_add_co_u32_e32 v4, vcc, s34, v2
	global_load_dwordx4 v[98:101], v[2:3], off
	s_nop 0
	v_addc_co_u32_e32 v5, vcc, 0, v3, vcc
	global_load_dwordx4 v[114:117], v[4:5], off
	global_load_dwordx4 v[102:105], v[2:3], off offset:1024
	global_load_dwordx4 v[118:121], v[4:5], off offset:1024
	global_load_dwordx4 v[106:109], v[2:3], off offset:2048
	global_load_dwordx4 v[122:125], v[4:5], off offset:2048
	global_load_dwordx4 v[110:113], v[2:3], off offset:3072
	global_load_dwordx4 v[126:129], v[4:5], off offset:3072
	v_mfma_f32_32x32x16_bf16 v[34:49], v[62:65], v[146:149], v[34:49]
	v_fma_f32 v18, v74, v22, v18
	v_fma_f32 v19, v75, v23, v19
	v_max_i32_e32 v22, 0, v28
	v_max_i32_e32 v23, 0, v29
	v_fma_f32 v18, v76, v22, v18
	v_fma_f32 v19, v77, v23, v19
	v_max_i32_e32 v22, 0, v30
	v_max_i32_e32 v23, 0, v31
	v_fma_f32 v18, v78, v22, v18
	v_fma_f32 v19, v79, v23, v19
	s_nop 2
	v_max_i32_e32 v34, 0, v34
	v_max_i32_e32 v35, 0, v35
	v_fma_f32 v34, v66, v34, 0
	v_fma_f32 v35, v67, v35, 0
	v_max_i32_e32 v36, 0, v36
	v_max_i32_e32 v37, 0, v37
	v_fma_f32 v20, v68, v36, v34
	v_fma_f32 v21, v69, v37, v35
	v_max_i32_e32 v34, 0, v38
	v_max_i32_e32 v35, 0, v39
	v_fma_f32 v20, v70, v34, v20
	v_fma_f32 v21, v71, v35, v21
	v_max_i32_e32 v24, 0, v40
	v_max_i32_e32 v25, 0, v41
	v_fma_f32 v20, v72, v24, v20
	v_fma_f32 v21, v73, v25, v21
	v_max_i32_e32 v24, 0, v42
	v_max_i32_e32 v25, 0, v43
	v_fma_f32 v20, v74, v24, v20
	v_fma_f32 v21, v75, v25, v21
	v_max_i32_e32 v24, 0, v44
	v_max_i32_e32 v25, 0, v45
	v_fma_f32 v20, v76, v24, v20
	v_fma_f32 v21, v77, v25, v21
	v_max_i32_e32 v24, 0, v46
	v_max_i32_e32 v25, 0, v47
	v_fma_f32 v20, v78, v24, v20
	v_fma_f32 v21, v79, v25, v21
	v_max_i32_e32 v22, 0, v32
	v_max_i32_e32 v23, 0, v33
	v_max_i32_e32 v24, 0, v48
	v_max_i32_e32 v25, 0, v49
	v_mfma_f32_32x32x16_bf16 v[2:17], v[50:53], v[14:17], 0
	v_fma_f32 v34, v80, v22, v18
	v_fma_f32 v35, v81, v23, v19
	v_fma_f32 v36, v80, v24, v20
	v_fma_f32 v37, v81, v25, v21
	v_add_f32_e32 v34, v34, v35
	v_mov_b32_e32 v35, v34
	v_add_f32_e32 v36, v36, v37
	v_mov_b32_e32 v37, v36
	s_waitcnt vmcnt(8)
; #define IDX_MMA(BX, cA, cB) do { _Pragma("unroll") for (int s = 0; s < 4; ++s) { cA = __builtin_amdgcn_mfma_f32_32x32x16_bf16(af[s], BX[s], cA, 0, 0, 0); cB = __builtin_amdgcn_mfma_f32_32x32x16_bf16(af[s], BX[4 + s], cB, 0, 0, 0); } } while (0)
; #define IDX_LOAD(BX, i_) do { const bf16_t* kn_ = kp + (size_t)(i_) * 4096; \
;         _Pragma("unroll") for (int s = 0; s < 4; ++s) { BX[s] = *(const bf16x8*)(kn_ + 512 * s); BX[4 + s] = *(const bf16x8*)(kn_ + 2048 + 512 * s); } } while (0)
; __device__ __forceinline__ unsigned sortable_u(float v) { const unsigned b = __float_as_uint(v); return (b & 0x80000000u) ? ~b : (b | 0x80000000u); }
; __device__ __forceinline__ void indexer_query(Frame& F, ArgsP a, int b, int t) {
;     ...
;     bf16x8 bX[8], bY[8];
;     IDX_LOAD(bX, 0); IDX_LOAD(bY, nt > 1 ? 1 : 0);
;     for (int i = 0; i < nt; i += 2) {
;         f32x16 cA = {}, cB = {}, cC = {}, cD = {};
;         IDX_MMA(bX, cA, cB); IDX_LOAD(bX, i + 2 < nt ? i + 2 : nt - 1);
;         IDX_MMA(bY, cC, cD); IDX_LOAD(bY, i + 3 < nt ? i + 3 : nt - 1);
;         IDX_SUM(cA, cB, i); IDX_SUM(cC, cD, i + 1);
	v_mov_b64_e32 v[148:149], v[144:145]
	v_permlane32_swap_b32_e32 v34, v36
	v_mfma_f32_32x32x16_bf16 v[18:33], v[50:53], v[162:165], 0
	v_mov_b64_e32 v[38:39], v[90:91]
	v_mov_b64_e32 v[42:43], v[86:87]
	v_mov_b64_e32 v[146:147], v[142:143]
	v_mov_b64_e32 v[40:41], v[92:93]
	v_mov_b64_e32 v[44:45], v[88:89]
	s_waitcnt vmcnt(6)
	v_mov_b64_e32 v[164:165], v[116:117]
	v_mfma_f32_32x32x16_bf16 v[2:17], v[54:57], v[174:177], v[2:17]
	s_waitcnt vmcnt(5)
	v_mov_b64_e32 v[176:177], v[104:105]
	v_mov_b64_e32 v[162:163], v[114:115]
	v_mov_b64_e32 v[174:175], v[102:103]
	v_mfma_f32_32x32x16_bf16 v[18:33], v[54:57], v[158:161], v[18:33]
	s_waitcnt vmcnt(4)
	v_mov_b64_e32 v[160:161], v[120:121]
	v_mov_b64_e32 v[158:159], v[118:119]
	v_mfma_f32_32x32x16_bf16 v[2:17], v[58:61], v[170:173], v[2:17]
	s_waitcnt vmcnt(3)
	v_mov_b64_e32 v[172:173], v[108:109]
	v_mov_b64_e32 v[170:171], v[106:107]
	v_mfma_f32_32x32x16_bf16 v[18:33], v[58:61], v[154:157], v[18:33]
	s_waitcnt vmcnt(2)
	v_mov_b64_e32 v[156:157], v[124:125]
	v_mov_b64_e32 v[154:155], v[122:123]
	v_mfma_f32_32x32x16_bf16 v[2:17], v[62:65], v[166:169], v[2:17]
	s_waitcnt vmcnt(1)
	v_mov_b64_e32 v[168:169], v[112:113]
	v_mov_b64_e32 v[166:167], v[110:111]
	v_mfma_f32_32x32x16_bf16 v[18:33], v[62:65], v[150:153], v[18:33]
	s_nop 7
	v_max_i32_e32 v2, 0, v2
	v_max_i32_e32 v3, 0, v3
	v_fma_f32 v2, v66, v2, 0
	v_fma_f32 v3, v67, v3, 0
	v_max_i32_e32 v4, 0, v4
	v_max_i32_e32 v5, 0, v5
	v_fma_f32 v2, v68, v4, v2
	v_fma_f32 v3, v69, v5, v3
	v_max_i32_e32 v6, 0, v6
	v_max_i32_e32 v18, 0, v18
	v_max_i32_e32 v19, 0, v19
	v_fma_f32 v18, v66, v18, 0
	v_fma_f32 v19, v67, v19, 0
	v_max_i32_e32 v20, 0, v20
	v_max_i32_e32 v21, 0, v21
	v_fma_f32 v4, v68, v20, v18
	v_fma_f32 v5, v69, v21, v19
	v_max_i32_e32 v7, 0, v7
	v_max_i32_e32 v18, 0, v22
	v_max_i32_e32 v19, 0, v23
	v_fma_f32 v2, v70, v6, v2
	v_fma_f32 v3, v71, v7, v3
	v_fma_f32 v4, v70, v18, v4
	v_fma_f32 v5, v71, v19, v5
	v_max_i32_e32 v6, 0, v8
	v_max_i32_e32 v7, 0, v9
	v_max_i32_e32 v8, 0, v24
	v_max_i32_e32 v9, 0, v25
	v_fma_f32 v2, v72, v6, v2
	v_fma_f32 v3, v73, v7, v3
	v_fma_f32 v4, v72, v8, v4
	v_fma_f32 v5, v73, v9, v5
	v_max_i32_e32 v6, 0, v10
	v_max_i32_e32 v7, 0, v11
	v_max_i32_e32 v8, 0, v26
	v_max_i32_e32 v9, 0, v27
	v_fma_f32 v2, v74, v6, v2
	v_fma_f32 v3, v75, v7, v3
	v_fma_f32 v4, v74, v8, v4
	v_fma_f32 v5, v75, v9, v5
	v_max_i32_e32 v6, 0, v12
	v_max_i32_e32 v7, 0, v13
	v_max_i32_e32 v8, 0, v28
	v_max_i32_e32 v9, 0, v29
	v_fma_f32 v2, v76, v6, v2
	v_fma_f32 v3, v77, v7, v3
	v_fma_f32 v4, v76, v8, v4
	v_fma_f32 v5, v77, v9, v5
	v_max_i32_e32 v6, 0, v14
	v_max_i32_e32 v7, 0, v15
	v_max_i32_e32 v8, 0, v30
	v_max_i32_e32 v9, 0, v31
	v_fma_f32 v2, v78, v6, v2
	v_fma_f32 v3, v79, v7, v3
	v_fma_f32 v4, v78, v8, v4
	v_fma_f32 v5, v79, v9, v5
	v_max_i32_e32 v6, 0, v16
	v_max_i32_e32 v7, 0, v17
	v_max_i32_e32 v8, 0, v32
	v_max_i32_e32 v9, 0, v33
	v_fma_f32 v2, v80, v6, v2
	v_fma_f32 v3, v81, v7, v3
	v_fma_f32 v4, v80, v8, v4
	v_fma_f32 v5, v81, v9, v5
	v_add_f32_e32 v2, v2, v3
	v_mov_b32_e32 v3, v2
	v_add_f32_e32 v4, v4, v5
	v_mov_b32_e32 v5, v4
	v_mov_b32_e32 v3, v34
	s_nop 0
	v_permlane32_swap_b32_e32 v2, v4
	v_mov_b32_e32 v5, v36
	v_add_f32_e32 v2, v2, v4
	v_add_f32_e32 v3, v3, v5
	v_mov_b64_e32 v[6:7], v[134:135]
	v_not_b32_e32 v4, v3
	v_cmp_gt_i32_e64 s[0:1], 0, v3
	v_cmp_gt_i32_e32 vcc, 0, v2
	v_mov_b64_e32 v[10:11], v[130:131]
	v_cndmask_b32_e64 v3, -|v3|, v4, s[0:1]
	v_not_b32_e32 v4, v2
	v_cndmask_b32_e64 v2, -|v2|, v4, vcc
	ds_write2st64_b32 v193, v3, v2 offset1:1
	v_mov_b64_e32 v[2:3], v[138:139]
	v_mov_b64_e32 v[34:35], v[94:95]
	v_mov_b64_e32 v[18:19], v[82:83]
	s_waitcnt vmcnt(0)
	v_mov_b64_e32 v[152:153], v[128:129]
	v_mov_b64_e32 v[14:15], v[98:99]
	v_add_u32_e32 v193, 0x200, v193
	v_mov_b64_e32 v[4:5], v[140:141]
	v_mov_b64_e32 v[8:9], v[136:137]
	v_mov_b64_e32 v[12:13], v[132:133]
	v_mov_b64_e32 v[36:37], v[96:97]
	v_mov_b64_e32 v[20:21], v[84:85]
	v_mov_b64_e32 v[150:151], v[126:127]
	v_mov_b64_e32 v[16:17], v[100:101]
	s_cbranch_scc1 .LBB0_720
